# K-loop phase-4 MFMA block moved to the same 4-mod-8 byte parity as the other three (one s_nop before its wait, one compensating s_nop after the loop)
# speedup vs baseline: 1.0023x; 1.0023x over previous
; #define PG8_LDA(dst, b, h) do { _Pragma("unroll") for (int m = 0; m < 4; ++m) _Pragma("unroll") for (int k = 0; k < 2; ++k) dst[m][k] = *(const LAS bf16x8*)(lds + PG8_SA(b, h) + aoff + m * 2048 + k * 1024); } while (0)
; #define PG8_LDB(dst, b, h) do { _Pragma("unroll") for (int n = 0; n < 2; ++n) _Pragma("unroll") for (int k = 0; k < 2; ++k) dst[n][k] = *(const LAS bf16x8*)(lds + PG8_SB(b, h) + boff + n * 2048 + k * 1024); } while (0)
; #define PG8_MMA(ai, bj, At, Bt) do { __builtin_amdgcn_s_setprio(1); _Pragma("unroll") for (int m = 0; m < 4; ++m) _Pragma("unroll") for (int n = 0; n < 2; ++n) _Pragma("unroll") for (int k = 0; k < 2; ++k) \
;         acc[ai][bj][m][n] = __builtin_amdgcn_mfma_f32_16x16x32_bf16(Bt[n][k], At[m][k], acc[ai][bj][m][n], 0, 0, 0); __builtin_amdgcn_s_setprio(0); } while (0)
; #define PG8_WAIT_V(n) asm volatile("s_waitcnt vmcnt(" #n ")" ::: "memory")
; #define PG8_WAIT_L(n) asm volatile("s_waitcnt lgkmcnt(" #n ")" ::: "memory")
; #define PG8_BAR __builtin_amdgcn_s_barrier()
; #define PG8_SCHED __builtin_amdgcn_sched_barrier(0)
; #define PG8_STA(bufoff, gbase, ld) PG8_STAGE(bufoff, gbase, RA0 * (unsigned)(ld) + CC0, RA1 * (unsigned)(ld) + CC1)
; __device__ __forceinline__ void gemm_phase(LAS unsigned char* lds, const Sched& S, const Epi& E) {
;     ...
;         for (int t = 0; t < nt_main; t += 2) {
;             const bool last = (t == nt - 2);
;             const char* a1 = cA + (size_t)(t + 1) * kstep;
;             const char* a2 = last ? nA : cA + (size_t)(t + 2) * kstep; const char* b2 = last ? nB : cB + (size_t)(t + 2) * kstep;
;             const char* a3 = a2 + kstep; const char* b3 = b2 + kstep;
;             const int xlda = last ? nlda : lda, xldb = last ? nldb : ldb;
;             const size_t xhA = (size_t)HALF * xlda * 2, xhB = (size_t)HALF * xldb * 2;
;             PG8_LDB(B0, 0, 0); PG8_LDB(B1, 0, 1); PG8_SCHED; PG8_LDA(At, 0, 0); PG8_STA(PG8_SA(1, 1), a1 + hA, lda);
;             PG8_WAIT_V(8); PG8_WAIT_L(0); PG8_BAR; PG8_MMA(0, 0, At, B0); PG8_MMA(0, 1, At, B1); PG8_BAR; PG8_SCHED;
;             PG8_LDA(At, 0, 1); PG8_STB(PG8_SB(0, 0), b2, xldb); PG8_STB(PG8_SB(0, 1), b2 + xhB, xldb); PG8_STA(PG8_SA(0, 0), a2, xlda);
;             PG8_WAIT_V(8); PG8_WAIT_L(0); PG8_BAR; PG8_MMA(1, 0, At, B0); PG8_MMA(1, 1, At, B1); PG8_BAR; PG8_SCHED;
.LBB0_263:
	s_add_i32 s24, s8, 2
	s_add_u32 s26, vcc_lo, 0x80
	s_addc_u32 s9, vcc_hi, 0
	s_add_i32 s37, 0, 0x10000
	s_cmp_eq_u32 s21, s8
	s_cselect_b32 s9, s7, s9
	s_cselect_b32 s8, s6, s26
	s_cselect_b32 s92, s11, s61
	s_cselect_b32 s30, s22, s20
	v_add_u32_e32 v0, s37, v241
	s_cselect_b32 s29, s13, s72
	s_cselect_b32 s28, s12, s2
	s_add_i32 s57, 0, 0x14000
	ds_read_b128 v[134:137], v0
	ds_read_b128 v[138:141], v0 offset:1024
	ds_read_b128 v[142:145], v0 offset:2048
	ds_read_b128 v[146:149], v0 offset:3072
	v_add_u32_e32 v0, s57, v241
	ds_read_b128 v[150:153], v0
	ds_read_b128 v[154:157], v0 offset:1024
	ds_read_b128 v[158:161], v0 offset:2048
	ds_read_b128 v[162:165], v0 offset:3072
	s_mov_b32 s93, s31
	s_lshl_b64 s[26:27], s[30:31], 8
	v_add_u32_e32 v0, 0, v240
	v_lshl_add_u64 v[214:215], vcc, 0, v[130:131]
	s_add_i32 m0, s34, 0xc000
	ds_read_b128 v[166:169], v0
	ds_read_b128 v[170:173], v0 offset:1024
	ds_read_b128 v[174:177], v0 offset:2048
	ds_read_b128 v[178:181], v0 offset:3072
	ds_read_b128 v[182:185], v0 offset:4096
	ds_read_b128 v[186:189], v0 offset:5120
	ds_read_b128 v[190:193], v0 offset:6144
	ds_read_b128 v[210:213], v0 offset:7168
	global_load_lds_dwordx4 v[214:215], off
	v_lshl_add_u64 v[214:215], vcc, 0, v[132:133]
	s_add_i32 m0, s34, 0xe000
	s_nop 0
	global_load_lds_dwordx4 v[214:215], off
	s_waitcnt vmcnt(8)
	s_waitcnt lgkmcnt(0)
	s_barrier
	s_setprio 1
	s_waitcnt lgkmcnt(0)
	v_mfma_f32_16x16x32_bf16 v[126:129], v[134:137], v[166:169], v[126:129]
	v_mfma_f32_16x16x32_bf16 v[122:125], v[142:145], v[166:169], v[122:125]
	v_mfma_f32_16x16x32_bf16 v[110:113], v[134:137], v[174:177], v[110:113]
	v_mfma_f32_16x16x32_bf16 v[106:109], v[142:145], v[174:177], v[106:109]
	v_mfma_f32_16x16x32_bf16 v[98:101], v[134:137], v[182:185], v[98:101]
	v_mfma_f32_16x16x32_bf16 v[90:93], v[142:145], v[182:185], v[90:93]
	v_mfma_f32_16x16x32_bf16 v[82:85], v[134:137], v[190:193], v[82:85]
	v_mfma_f32_16x16x32_bf16 v[74:77], v[142:145], v[190:193], v[74:77]
	v_mfma_f32_16x16x32_bf16 v[126:129], v[138:141], v[170:173], v[126:129]
	v_mfma_f32_16x16x32_bf16 v[122:125], v[146:149], v[170:173], v[122:125]
	v_mfma_f32_16x16x32_bf16 v[110:113], v[138:141], v[178:181], v[110:113]
	v_mfma_f32_16x16x32_bf16 v[106:109], v[146:149], v[178:181], v[106:109]
	v_mfma_f32_16x16x32_bf16 v[98:101], v[138:141], v[186:189], v[98:101]
	v_mfma_f32_16x16x32_bf16 v[90:93], v[146:149], v[186:189], v[90:93]
	v_mfma_f32_16x16x32_bf16 v[82:85], v[138:141], v[210:213], v[82:85]
	v_mfma_f32_16x16x32_bf16 v[74:77], v[146:149], v[210:213], v[74:77]
	s_setprio 0
	s_setprio 1
	v_mfma_f32_16x16x32_bf16 v[118:121], v[150:153], v[166:169], v[118:121]
	v_mfma_f32_16x16x32_bf16 v[114:117], v[158:161], v[166:169], v[114:117]
	v_mfma_f32_16x16x32_bf16 v[102:105], v[150:153], v[174:177], v[102:105]
	v_mfma_f32_16x16x32_bf16 v[94:97], v[158:161], v[174:177], v[94:97]
	v_mfma_f32_16x16x32_bf16 v[86:89], v[150:153], v[182:185], v[86:89]
	v_mfma_f32_16x16x32_bf16 v[78:81], v[158:161], v[182:185], v[78:81]
	v_mfma_f32_16x16x32_bf16 v[70:73], v[150:153], v[190:193], v[70:73]
	v_mfma_f32_16x16x32_bf16 v[66:69], v[158:161], v[190:193], v[66:69]
	v_mfma_f32_16x16x32_bf16 v[118:121], v[154:157], v[170:173], v[118:121]
	v_mfma_f32_16x16x32_bf16 v[114:117], v[162:165], v[170:173], v[114:117]
	v_mfma_f32_16x16x32_bf16 v[102:105], v[154:157], v[178:181], v[102:105]
	v_mfma_f32_16x16x32_bf16 v[94:97], v[162:165], v[178:181], v[94:97]
	v_mfma_f32_16x16x32_bf16 v[86:89], v[154:157], v[186:189], v[86:89]
	v_mfma_f32_16x16x32_bf16 v[78:81], v[162:165], v[186:189], v[78:81]
	v_mfma_f32_16x16x32_bf16 v[70:73], v[154:157], v[210:213], v[70:73]
	v_mfma_f32_16x16x32_bf16 v[66:69], v[162:165], v[210:213], v[66:69]
	s_setprio 0
	s_barrier
	s_add_i32 s37, s37, s25
	v_mad_u64_u32 v[214:215], s[80:81], s92, v237, v[194:195]
	s_mov_b32 m0, s37
	ds_read_b128 v[166:169], v0 offset:16384
	ds_read_b128 v[170:173], v0 offset:17408
	ds_read_b128 v[174:177], v0 offset:18432
	ds_read_b128 v[178:181], v0 offset:19456
	ds_read_b128 v[182:185], v0 offset:20480
	ds_read_b128 v[186:189], v0 offset:21504
	ds_read_b128 v[190:193], v0 offset:22528
	ds_read_b128 v[210:213], v0 offset:23552
	s_lshl_b64 s[74:75], s[92:93], 8
	global_load_lds_dwordx4 v214, s[28:29]
	s_add_i32 m0, s37, 0x2000
	s_add_u32 s74, s28, s74
	v_mad_u64_u32 v[216:217], s[80:81], s92, v238, v[196:197]
	s_addc_u32 s75, s29, s75
	s_add_i32 s37, s57, s25
	global_load_lds_dwordx4 v216, s[28:29]
	s_mov_b32 m0, s37
	v_mad_u64_u32 v[218:219], s[80:81], s30, v235, v[194:195]
	global_load_lds_dwordx4 v214, s[74:75]
	s_add_i32 m0, s37, 0x2000
	v_mad_u64_u32 v[220:221], s[80:81], s30, v236, v[196:197]
	global_load_lds_dwordx4 v216, s[74:75]
	s_mov_b32 m0, s34
	v_mov_b32_e32 v215, v1
	global_load_lds_dwordx4 v218, s[8:9]
	s_mov_b32 m0, s35
	v_mov_b32_e32 v217, v1
	global_load_lds_dwordx4 v220, s[8:9]
	v_mov_b32_e32 v219, v1
	v_mov_b32_e32 v221, v1
	v_lshl_add_u64 v[222:223], s[28:29], 0, v[214:215]
	v_lshl_add_u64 v[224:225], s[28:29], 0, v[216:217]
	v_lshl_add_u64 v[214:215], s[74:75], 0, v[214:215]
	v_lshl_add_u64 v[216:217], s[74:75], 0, v[216:217]
	v_lshl_add_u64 v[226:227], s[8:9], 0, v[218:219]
	v_lshl_add_u64 v[228:229], s[8:9], 0, v[220:221]
	s_waitcnt vmcnt(8)
	s_waitcnt lgkmcnt(0)
	s_barrier
; #define PG8_LDA(dst, b, h) do { _Pragma("unroll") for (int m = 0; m < 4; ++m) _Pragma("unroll") for (int k = 0; k < 2; ++k) dst[m][k] = *(const LAS bf16x8*)(lds + PG8_SA(b, h) + aoff + m * 2048 + k * 1024); } while (0)
; #define PG8_LDB(dst, b, h) do { _Pragma("unroll") for (int n = 0; n < 2; ++n) _Pragma("unroll") for (int k = 0; k < 2; ++k) dst[n][k] = *(const LAS bf16x8*)(lds + PG8_SB(b, h) + boff + n * 2048 + k * 1024); } while (0)
; #define PG8_MMA(ai, bj, At, Bt) do { __builtin_amdgcn_s_setprio(1); _Pragma("unroll") for (int m = 0; m < 4; ++m) _Pragma("unroll") for (int n = 0; n < 2; ++n) _Pragma("unroll") for (int k = 0; k < 2; ++k) \
;         acc[ai][bj][m][n] = __builtin_amdgcn_mfma_f32_16x16x32_bf16(Bt[n][k], At[m][k], acc[ai][bj][m][n], 0, 0, 0); __builtin_amdgcn_s_setprio(0); } while (0)
; #define PG8_WAIT_V(n) asm volatile("s_waitcnt vmcnt(" #n ")" ::: "memory")
; #define PG8_WAIT_L(n) asm volatile("s_waitcnt lgkmcnt(" #n ")" ::: "memory")
; #define PG8_BAR __builtin_amdgcn_s_barrier()
; #define PG8_SCHED __builtin_amdgcn_sched_barrier(0)
; #define PG8_STA(bufoff, gbase, ld) PG8_STAGE(bufoff, gbase, RA0 * (unsigned)(ld) + CC0, RA1 * (unsigned)(ld) + CC1)
; #define PG8_STB(bufoff, gbase, ld) PG8_STAGE(bufoff, gbase, RB0 * (unsigned)(ld) + CC0, RB1 * (unsigned)(ld) + CC1)
; __device__ __forceinline__ void gemm_phase(LAS unsigned char* lds, const Sched& S, const Epi& E) {
;     ...
;             PG8_WAIT_V(8); PG8_WAIT_L(0); PG8_BAR; PG8_MMA(1, 0, At, B0); PG8_MMA(1, 1, At, B1); PG8_BAR; PG8_SCHED;
;             PG8_LDB(B0, 1, 0); PG8_LDB(B1, 1, 1); PG8_SCHED; PG8_LDA(At, 1, 0); PG8_STA(PG8_SA(0, 1), a2 + xhA, xlda);
;             PG8_WAIT_V(8); PG8_WAIT_L(0); PG8_BAR; PG8_MMA(0, 0, At, B0); PG8_MMA(0, 1, At, B1); PG8_BAR; PG8_SCHED;
;             PG8_LDA(At, 1, 1); PG8_STB(PG8_SB(1, 0), b3, xldb); PG8_STB(PG8_SB(1, 1), b3 + xhB, xldb); PG8_STA(PG8_SA(1, 0), a3, xlda);
;             PG8_WAIT_V(8); PG8_WAIT_L(0); PG8_BAR; PG8_MMA(1, 0, At, B0); PG8_MMA(1, 1, At, B1); PG8_BAR; PG8_SCHED;
	s_setprio 1
	s_waitcnt lgkmcnt(0)
	v_mfma_f32_16x16x32_bf16 v[62:65], v[134:137], v[166:169], v[62:65]
	v_mfma_f32_16x16x32_bf16 v[58:61], v[142:145], v[166:169], v[58:61]
	v_mfma_f32_16x16x32_bf16 v[46:49], v[134:137], v[174:177], v[46:49]
	v_mfma_f32_16x16x32_bf16 v[42:45], v[142:145], v[174:177], v[42:45]
	v_mfma_f32_16x16x32_bf16 v[30:33], v[134:137], v[182:185], v[30:33]
	v_mfma_f32_16x16x32_bf16 v[26:29], v[142:145], v[182:185], v[26:29]
	v_mfma_f32_16x16x32_bf16 v[14:17], v[134:137], v[190:193], v[14:17]
	v_mfma_f32_16x16x32_bf16 v[10:13], v[142:145], v[190:193], v[10:13]
	v_mfma_f32_16x16x32_bf16 v[62:65], v[138:141], v[170:173], v[62:65]
	v_mfma_f32_16x16x32_bf16 v[58:61], v[146:149], v[170:173], v[58:61]
	v_mfma_f32_16x16x32_bf16 v[46:49], v[138:141], v[178:181], v[46:49]
	v_mfma_f32_16x16x32_bf16 v[42:45], v[146:149], v[178:181], v[42:45]
	v_mfma_f32_16x16x32_bf16 v[30:33], v[138:141], v[186:189], v[30:33]
	v_mfma_f32_16x16x32_bf16 v[26:29], v[146:149], v[186:189], v[26:29]
	v_mfma_f32_16x16x32_bf16 v[14:17], v[138:141], v[210:213], v[14:17]
	v_mfma_f32_16x16x32_bf16 v[10:13], v[146:149], v[210:213], v[10:13]
	s_setprio 0
	s_setprio 1
	v_mfma_f32_16x16x32_bf16 v[54:57], v[150:153], v[166:169], v[54:57]
	v_mfma_f32_16x16x32_bf16 v[50:53], v[158:161], v[166:169], v[50:53]
	v_mfma_f32_16x16x32_bf16 v[38:41], v[150:153], v[174:177], v[38:41]
	v_mfma_f32_16x16x32_bf16 v[34:37], v[158:161], v[174:177], v[34:37]
	v_mfma_f32_16x16x32_bf16 v[22:25], v[150:153], v[182:185], v[22:25]
	v_mfma_f32_16x16x32_bf16 v[18:21], v[158:161], v[182:185], v[18:21]
	v_mfma_f32_16x16x32_bf16 v[6:9], v[150:153], v[190:193], v[6:9]
	v_mfma_f32_16x16x32_bf16 v[2:5], v[158:161], v[190:193], v[2:5]
	v_mfma_f32_16x16x32_bf16 v[54:57], v[154:157], v[170:173], v[54:57]
	v_mfma_f32_16x16x32_bf16 v[50:53], v[162:165], v[170:173], v[50:53]
	v_mfma_f32_16x16x32_bf16 v[38:41], v[154:157], v[178:181], v[38:41]
	v_mfma_f32_16x16x32_bf16 v[34:37], v[162:165], v[178:181], v[34:37]
	v_mfma_f32_16x16x32_bf16 v[22:25], v[154:157], v[186:189], v[22:25]
	v_mfma_f32_16x16x32_bf16 v[18:21], v[162:165], v[186:189], v[18:21]
	v_mfma_f32_16x16x32_bf16 v[6:9], v[154:157], v[210:213], v[6:9]
	v_mfma_f32_16x16x32_bf16 v[2:5], v[162:165], v[210:213], v[2:5]
	s_setprio 0
	s_barrier
	s_add_i32 s28, 0, 0x18000
	s_add_i32 s29, 0, 0x1c000
	v_add_u32_e32 v146, s28, v241
	v_add_u32_e32 v162, s29, v241
	ds_read_b128 v[134:137], v146
	ds_read_b128 v[138:141], v146 offset:1024
	ds_read_b128 v[142:145], v146 offset:2048
	ds_read_b128 v[146:149], v146 offset:3072
	ds_read_b128 v[150:153], v162
	ds_read_b128 v[154:157], v162 offset:1024
	ds_read_b128 v[158:161], v162 offset:2048
	ds_read_b128 v[162:165], v162 offset:3072
	s_add_u32 s8, s8, s26
	s_addc_u32 s9, s9, s27
	s_mov_b32 m0, s39
	ds_read_b128 v[166:169], v0 offset:32768
	ds_read_b128 v[170:173], v0 offset:33792
	ds_read_b128 v[174:177], v0 offset:34816
	ds_read_b128 v[178:181], v0 offset:35840
	ds_read_b128 v[182:185], v0 offset:36864
	ds_read_b128 v[186:189], v0 offset:37888
	ds_read_b128 v[190:193], v0 offset:38912
	ds_read_b128 v[210:213], v0 offset:39936
	global_load_lds_dwordx4 v218, s[8:9]
	s_mov_b32 m0, s91
	s_nop 0
	global_load_lds_dwordx4 v220, s[8:9]
	s_waitcnt vmcnt(8)
	s_waitcnt lgkmcnt(0)
	s_barrier
	s_setprio 1
	s_waitcnt lgkmcnt(0)
	v_mfma_f32_16x16x32_bf16 v[126:129], v[134:137], v[166:169], v[126:129]
	v_mfma_f32_16x16x32_bf16 v[122:125], v[142:145], v[166:169], v[122:125]
	v_mfma_f32_16x16x32_bf16 v[110:113], v[134:137], v[174:177], v[110:113]
	v_mfma_f32_16x16x32_bf16 v[106:109], v[142:145], v[174:177], v[106:109]
	v_mfma_f32_16x16x32_bf16 v[98:101], v[134:137], v[182:185], v[98:101]
	v_mfma_f32_16x16x32_bf16 v[90:93], v[142:145], v[182:185], v[90:93]
	v_mfma_f32_16x16x32_bf16 v[82:85], v[134:137], v[190:193], v[82:85]
	v_mfma_f32_16x16x32_bf16 v[74:77], v[142:145], v[190:193], v[74:77]
	v_mfma_f32_16x16x32_bf16 v[126:129], v[138:141], v[170:173], v[126:129]
	v_mfma_f32_16x16x32_bf16 v[122:125], v[146:149], v[170:173], v[122:125]
	v_mfma_f32_16x16x32_bf16 v[110:113], v[138:141], v[178:181], v[110:113]
	v_mfma_f32_16x16x32_bf16 v[106:109], v[146:149], v[178:181], v[106:109]
	v_mfma_f32_16x16x32_bf16 v[98:101], v[138:141], v[186:189], v[98:101]
	v_mfma_f32_16x16x32_bf16 v[90:93], v[146:149], v[186:189], v[90:93]
	v_mfma_f32_16x16x32_bf16 v[82:85], v[138:141], v[210:213], v[82:85]
	v_mfma_f32_16x16x32_bf16 v[74:77], v[146:149], v[210:213], v[74:77]
	s_setprio 0
	s_setprio 1
	v_mfma_f32_16x16x32_bf16 v[118:121], v[150:153], v[166:169], v[118:121]
	v_mfma_f32_16x16x32_bf16 v[114:117], v[158:161], v[166:169], v[114:117]
	v_mfma_f32_16x16x32_bf16 v[102:105], v[150:153], v[174:177], v[102:105]
	v_mfma_f32_16x16x32_bf16 v[94:97], v[158:161], v[174:177], v[94:97]
	v_mfma_f32_16x16x32_bf16 v[86:89], v[150:153], v[182:185], v[86:89]
	v_mfma_f32_16x16x32_bf16 v[78:81], v[158:161], v[182:185], v[78:81]
	v_mfma_f32_16x16x32_bf16 v[70:73], v[150:153], v[190:193], v[70:73]
	v_mfma_f32_16x16x32_bf16 v[66:69], v[158:161], v[190:193], v[66:69]
	v_mfma_f32_16x16x32_bf16 v[118:121], v[154:157], v[170:173], v[118:121]
	v_mfma_f32_16x16x32_bf16 v[114:117], v[162:165], v[170:173], v[114:117]
	v_mfma_f32_16x16x32_bf16 v[102:105], v[154:157], v[178:181], v[102:105]
	v_mfma_f32_16x16x32_bf16 v[94:97], v[162:165], v[178:181], v[94:97]
	v_mfma_f32_16x16x32_bf16 v[86:89], v[154:157], v[186:189], v[86:89]
	v_mfma_f32_16x16x32_bf16 v[78:81], v[162:165], v[186:189], v[78:81]
	v_mfma_f32_16x16x32_bf16 v[70:73], v[154:157], v[210:213], v[70:73]
	v_mfma_f32_16x16x32_bf16 v[66:69], v[162:165], v[210:213], v[66:69]
	s_setprio 0
	s_barrier
; #define PG8_LDA(dst, b, h) do { _Pragma("unroll") for (int m = 0; m < 4; ++m) _Pragma("unroll") for (int k = 0; k < 2; ++k) dst[m][k] = *(const LAS bf16x8*)(lds + PG8_SA(b, h) + aoff + m * 2048 + k * 1024); } while (0)
; #define PG8_MMA(ai, bj, At, Bt) do { __builtin_amdgcn_s_setprio(1); _Pragma("unroll") for (int m = 0; m < 4; ++m) _Pragma("unroll") for (int n = 0; n < 2; ++n) _Pragma("unroll") for (int k = 0; k < 2; ++k) \
;         acc[ai][bj][m][n] = __builtin_amdgcn_mfma_f32_16x16x32_bf16(Bt[n][k], At[m][k], acc[ai][bj][m][n], 0, 0, 0); __builtin_amdgcn_s_setprio(0); } while (0)
; #define PG8_WAIT_V(n) asm volatile("s_waitcnt vmcnt(" #n ")" ::: "memory")
; #define PG8_WAIT_L(n) asm volatile("s_waitcnt lgkmcnt(" #n ")" ::: "memory")
; #define PG8_BAR __builtin_amdgcn_s_barrier()
; #define PG8_SCHED __builtin_amdgcn_sched_barrier(0)
; #define PG8_STA(bufoff, gbase, ld) PG8_STAGE(bufoff, gbase, RA0 * (unsigned)(ld) + CC0, RA1 * (unsigned)(ld) + CC1)
; #define PG8_STB(bufoff, gbase, ld) PG8_STAGE(bufoff, gbase, RB0 * (unsigned)(ld) + CC0, RB1 * (unsigned)(ld) + CC1)
; __device__ __forceinline__ void gemm_phase(LAS unsigned char* lds, const Sched& S, const Epi& E) {
;     ...
;             PG8_LDA(At, 1, 1); PG8_STB(PG8_SB(1, 0), b3, xldb); PG8_STB(PG8_SB(1, 1), b3 + xhB, xldb); PG8_STA(PG8_SA(1, 0), a3, xlda);
;             PG8_WAIT_V(8); PG8_WAIT_L(0); PG8_BAR; PG8_MMA(1, 0, At, B0); PG8_MMA(1, 1, At, B1); PG8_BAR; PG8_SCHED;
;         }
	s_add_i32 s8, s28, s25
	v_lshl_add_u64 v[218:219], v[222:223], 0, s[52:53]
	s_mov_b32 m0, s8
	ds_read_b128 v[166:169], v0 offset:49152
	ds_read_b128 v[170:173], v0 offset:50176
	ds_read_b128 v[174:177], v0 offset:51200
	ds_read_b128 v[178:181], v0 offset:52224
	ds_read_b128 v[182:185], v0 offset:53248
	ds_read_b128 v[186:189], v0 offset:54272
	ds_read_b128 v[190:193], v0 offset:55296
	ds_read_b128 v[210:213], v0 offset:56320
	global_load_lds_dwordx4 v[218:219], off
	v_lshl_add_u64 v[218:219], v[224:225], 0, s[52:53]
	s_add_i32 m0, s8, 0x2000
	s_add_i32 s8, s29, s25
	global_load_lds_dwordx4 v[218:219], off
	v_lshl_add_u64 v[214:215], v[214:215], 0, s[52:53]
	s_mov_b32 m0, s8
	s_nop 0
	global_load_lds_dwordx4 v[214:215], off
	v_lshl_add_u64 v[214:215], v[216:217], 0, s[52:53]
	s_add_i32 m0, s8, 0x2000
	s_nop 0
	global_load_lds_dwordx4 v[214:215], off
	v_lshl_add_u64 v[214:215], v[226:227], 0, s[52:53]
	s_mov_b32 m0, s90
	s_nop 0
	global_load_lds_dwordx4 v[214:215], off
	v_lshl_add_u64 v[214:215], v[228:229], 0, s[52:53]
	s_mov_b32 m0, s73
	s_nop 0
	global_load_lds_dwordx4 v[214:215], off
	s_nop 0
	s_waitcnt vmcnt(8)
	s_waitcnt lgkmcnt(0)
	s_barrier
	s_setprio 1
	s_waitcnt lgkmcnt(0)
	v_mfma_f32_16x16x32_bf16 v[62:65], v[134:137], v[166:169], v[62:65]
	v_mfma_f32_16x16x32_bf16 v[58:61], v[142:145], v[166:169], v[58:61]
	v_mfma_f32_16x16x32_bf16 v[46:49], v[134:137], v[174:177], v[46:49]
	v_mfma_f32_16x16x32_bf16 v[42:45], v[142:145], v[174:177], v[42:45]
	v_mfma_f32_16x16x32_bf16 v[30:33], v[134:137], v[182:185], v[30:33]
	v_mfma_f32_16x16x32_bf16 v[26:29], v[142:145], v[182:185], v[26:29]
	v_mfma_f32_16x16x32_bf16 v[14:17], v[134:137], v[190:193], v[14:17]
	v_mfma_f32_16x16x32_bf16 v[10:13], v[142:145], v[190:193], v[10:13]
	v_mfma_f32_16x16x32_bf16 v[62:65], v[138:141], v[170:173], v[62:65]
	v_mfma_f32_16x16x32_bf16 v[58:61], v[146:149], v[170:173], v[58:61]
	v_mfma_f32_16x16x32_bf16 v[46:49], v[138:141], v[178:181], v[46:49]
	v_mfma_f32_16x16x32_bf16 v[42:45], v[146:149], v[178:181], v[42:45]
	v_mfma_f32_16x16x32_bf16 v[30:33], v[138:141], v[186:189], v[30:33]
	v_mfma_f32_16x16x32_bf16 v[26:29], v[146:149], v[186:189], v[26:29]
	v_mfma_f32_16x16x32_bf16 v[14:17], v[138:141], v[210:213], v[14:17]
	v_mfma_f32_16x16x32_bf16 v[10:13], v[146:149], v[210:213], v[10:13]
	s_setprio 0
	s_setprio 1
	v_mfma_f32_16x16x32_bf16 v[54:57], v[150:153], v[166:169], v[54:57]
	v_mfma_f32_16x16x32_bf16 v[50:53], v[158:161], v[166:169], v[50:53]
	v_mfma_f32_16x16x32_bf16 v[38:41], v[150:153], v[174:177], v[38:41]
	v_mfma_f32_16x16x32_bf16 v[34:37], v[158:161], v[174:177], v[34:37]
	v_mfma_f32_16x16x32_bf16 v[22:25], v[150:153], v[182:185], v[22:25]
	v_mfma_f32_16x16x32_bf16 v[18:21], v[158:161], v[182:185], v[18:21]
	v_mfma_f32_16x16x32_bf16 v[6:9], v[150:153], v[190:193], v[6:9]
	v_mfma_f32_16x16x32_bf16 v[2:5], v[158:161], v[190:193], v[2:5]
	v_mfma_f32_16x16x32_bf16 v[54:57], v[154:157], v[170:173], v[54:57]
	v_mfma_f32_16x16x32_bf16 v[50:53], v[162:165], v[170:173], v[50:53]
	v_mfma_f32_16x16x32_bf16 v[38:41], v[154:157], v[178:181], v[38:41]
	v_mfma_f32_16x16x32_bf16 v[34:37], v[162:165], v[178:181], v[34:37]
	v_mfma_f32_16x16x32_bf16 v[22:25], v[154:157], v[186:189], v[22:25]
	v_mfma_f32_16x16x32_bf16 v[18:21], v[162:165], v[186:189], v[18:21]
	v_mfma_f32_16x16x32_bf16 v[6:9], v[154:157], v[210:213], v[6:9]
	v_mfma_f32_16x16x32_bf16 v[2:5], v[162:165], v[210:213], v[2:5]
	s_setprio 0
	s_barrier
	s_add_u32 vcc_lo, vcc_lo, 0x100
	s_addc_u32 vcc_hi, vcc_hi, 0
	s_add_u32 s2, s2, 0x100
	s_addc_u32 s72, s72, 0
	s_cmp_ge_i32 s24, s68
	s_mov_b32 s8, s24
	s_cbranch_scc0 .LBB0_263
	s_nop 0
	s_mov_b32 s92, s3
	s_movk_i32 s93, 0x3fff
	s_movk_i32 s3, 0x2000
	s_and_b64 vcc, exec, s[44:45]
	s_cbranch_vccz .LBB0_266
